# dense attention: next tile's K LDS reads issued at the start of the softmax segment instead of its end, rest as v51
# speedup vs baseline: 1.0095x; 1.0095x over previous
; __device__ __forceinline__ void partialSM(f32x16& p0, f32x16& p1, float& m_reg, float& mn, float& alpha) {
;     ...
;   for (int r = 0; r < 16; ++r) p0[r] = __builtin_amdgcn_exp2f(p0[r]);
; }
; __device__ __forceinline__ void finishSM(f32x16& p0, f32x16& p1, float alpha, float& l_reg, bf16x8& pa0, bf16x8& pa1, bf16x8& pa2, bf16x8& pa3) {
; #pragma unroll
;   for (int r = 0; r < 16; ++r) p1[r] = __builtin_amdgcn_exp2f(p1[r]);
;   float ps = 0;
; #pragma unroll
;   for (int r = 0; r < 16; ++r) ps += p0[r];
; #pragma unroll
;   for (int r = 0; r < 16; ++r) ps += p1[r];
;   { auto rr = __builtin_amdgcn_permlane32_swap(__float_as_uint(ps), __float_as_uint(ps), false, false);
;     ps = __uint_as_float(rr[0]) + __uint_as_float(rr[1]); }
;   l_reg = l_reg * alpha + ps;
;     ...
;   PK4(p0, 0, pa0); PK4(p0, 8, pa1); PK4(p1, 0, pa2); PK4(p1, 8, pa3);
;     ...
; }
; __device__ __forceinline__ void qkt(f32x16& p0, f32x16& p1, const bf16_t* Ks, const bf16x8* qr, int r32, int hi) {
;   p0 = f32x16{}; p1 = f32x16{};
; #pragma unroll
;   for (int d0 = 0; d0 < 8; ++d0) { int cb = (d0 * 16 + hi * 8) * 2;
;     bf16x8 b0 = *reinterpret_cast<const bf16x8*>((const char*)Ks + KSWZ(r32, cb));
;     bf16x8 b1 = *reinterpret_cast<const bf16x8*>((const char*)Ks + KSWZ(32 + r32, cb));
;     p0 = __builtin_amdgcn_mfma_f32_32x32x16_bf16(b0, qr[d0], p0, 0, 0, 0);
;     p1 = __builtin_amdgcn_mfma_f32_32x32x16_bf16(b1, qr[d0], p1, 0, 0, 0); }
; }
.Lda_noresc_0:
	s_cmp_lt_u32 s31, 131
	s_cbranch_scc0 .Lda_skipk_0
	ds_read_b128 v[150:153], v204 offset:16384
	ds_read_b128 v[154:157], v204 offset:24576
	ds_read_b128 v[158:161], v205 offset:16384
	ds_read_b128 v[162:165], v205 offset:24576
	ds_read_b128 v[228:231], v206 offset:16384
	ds_read_b128 v[232:235], v206 offset:24576
	ds_read_b128 v[236:239], v207 offset:16384
	ds_read_b128 v[240:243], v207 offset:24576
.Lda_skipk_0:
	v_exp_f32_e32 v80, v80
	v_exp_f32_e32 v81, v81
	v_exp_f32_e32 v82, v82
	v_exp_f32_e32 v83, v83
	v_exp_f32_e32 v84, v84
	v_exp_f32_e32 v85, v85
	v_exp_f32_e32 v86, v86
	v_exp_f32_e32 v87, v87
	v_exp_f32_e32 v88, v88
	v_exp_f32_e32 v89, v89
	v_exp_f32_e32 v90, v90
	v_exp_f32_e32 v91, v91
	v_exp_f32_e32 v92, v92
	v_exp_f32_e32 v93, v93
	v_exp_f32_e32 v94, v94
	v_exp_f32_e32 v95, v95
	v_exp_f32_e32 v64, v64
	v_exp_f32_e32 v65, v65
	v_exp_f32_e32 v66, v66
	v_exp_f32_e32 v67, v67
	v_exp_f32_e32 v68, v68
	v_exp_f32_e32 v69, v69
	v_exp_f32_e32 v70, v70
	v_exp_f32_e32 v71, v71
	v_exp_f32_e32 v72, v72
	v_exp_f32_e32 v73, v73
	v_exp_f32_e32 v74, v74
	v_exp_f32_e32 v75, v75
	v_exp_f32_e32 v76, v76
	v_exp_f32_e32 v77, v77
	v_exp_f32_e32 v78, v78
	v_exp_f32_e32 v79, v79
	v_add_f32_e32 v190, v80, v81
	v_add_f32_e32 v191, v82, v83
	v_add_f32_e32 v190, v190, v84
	v_add_f32_e32 v191, v191, v85
	v_add_f32_e32 v190, v190, v86
	v_add_f32_e32 v191, v191, v87
	v_add_f32_e32 v190, v190, v88
	v_add_f32_e32 v191, v191, v89
	v_add_f32_e32 v190, v190, v90
	v_add_f32_e32 v191, v191, v91
	v_add_f32_e32 v190, v190, v92
	v_add_f32_e32 v191, v191, v93
	v_add_f32_e32 v190, v190, v94
	v_add_f32_e32 v191, v191, v95
	v_add_f32_e32 v190, v190, v64
	v_add_f32_e32 v191, v191, v65
	v_add_f32_e32 v190, v190, v66
	v_add_f32_e32 v191, v191, v67
	v_add_f32_e32 v190, v190, v68
	v_add_f32_e32 v191, v191, v69
	v_add_f32_e32 v190, v190, v70
	v_add_f32_e32 v191, v191, v71
	v_add_f32_e32 v190, v190, v72
	v_add_f32_e32 v191, v191, v73
	v_add_f32_e32 v190, v190, v74
	v_add_f32_e32 v191, v191, v75
	v_add_f32_e32 v190, v190, v76
	v_add_f32_e32 v191, v191, v77
	v_add_f32_e32 v190, v190, v78
	v_add_f32_e32 v191, v191, v79
	v_add_f32_e32 v190, v190, v191
	v_cvt_pk_bf16_f32 v166, v80, v81
	v_cvt_pk_bf16_f32 v167, v82, v83
	v_cvt_pk_bf16_f32 v168, v84, v85
	v_cvt_pk_bf16_f32 v169, v86, v87
	v_cvt_pk_bf16_f32 v170, v88, v89
	v_cvt_pk_bf16_f32 v171, v90, v91
	v_cvt_pk_bf16_f32 v172, v92, v93
	v_cvt_pk_bf16_f32 v173, v94, v95
	v_cvt_pk_bf16_f32 v176, v64, v65
	v_cvt_pk_bf16_f32 v177, v66, v67
	v_cvt_pk_bf16_f32 v178, v68, v69
	v_cvt_pk_bf16_f32 v179, v70, v71
	v_cvt_pk_bf16_f32 v180, v72, v73
	v_cvt_pk_bf16_f32 v181, v74, v75
	v_cvt_pk_bf16_f32 v182, v76, v77
	v_cvt_pk_bf16_f32 v183, v78, v79
	v_permlane32_swap_b32_e32 v166, v168
	v_permlane32_swap_b32_e32 v167, v169
	v_permlane32_swap_b32_e32 v170, v172
	v_permlane32_swap_b32_e32 v171, v173
	v_permlane32_swap_b32_e32 v176, v178
	v_permlane32_swap_b32_e32 v177, v179
	v_permlane32_swap_b32_e32 v180, v182
	v_permlane32_swap_b32_e32 v181, v183
	v_add_f32_e32 v175, v175, v190
	s_add_u32 s31, s31, 1
	s_barrier
	s_setprio 3
	s_waitcnt vmcnt(4)
	ds_write_b128 v197, v[186:189] offset:49152
	ds_write_b128 v197, v[220:223] offset:57344
	ds_write_b128 v185, v[246:249] offset:49152
	ds_write_b128 v185, v[200:203] offset:57344
	s_waitcnt lgkmcnt(10)
	v_mfma_f32_32x32x16_bf16 v[80:95], v[150:153], v[130:133], 0
	v_mfma_f32_32x32x16_bf16 v[64:79], v[154:157], v[130:133], 0
	global_load_dwordx4 v[186:189], v184, s[16:17]
	global_load_dwordx4 v[220:223], v184, s[2:3]
	global_load_dwordx4 v[246:249], v184, s[14:15]
	global_load_dwordx4 v[200:203], v184, s[10:11]
	s_add_u32 s16, s16, 0x60000
	s_addc_u32 s17, s17, 0
	s_add_u32 s2, s2, 0x60000
	s_addc_u32 s3, s3, 0
	s_add_u32 s14, s14, 0x60000
	s_addc_u32 s15, s15, 0
	s_add_u32 s10, s10, 0x60000
	s_addc_u32 s11, s11, 0
	ds_read_b128 v[150:153], v208 offset:16384
	ds_read_b128 v[154:157], v208 offset:24576
	s_waitcnt lgkmcnt(10)
	v_mfma_f32_32x32x16_bf16 v[80:95], v[158:161], v[126:129], v[80:95]
	v_mfma_f32_32x32x16_bf16 v[64:79], v[162:165], v[126:129], v[64:79]
	ds_read_b128 v[158:161], v209 offset:16384
	ds_read_b128 v[162:165], v209 offset:24576
	s_waitcnt lgkmcnt(10)
	v_mfma_f32_32x32x16_bf16 v[80:95], v[228:231], v[122:125], v[80:95]
	v_mfma_f32_32x32x16_bf16 v[64:79], v[232:235], v[122:125], v[64:79]
	ds_read_b128 v[228:231], v210 offset:16384
	ds_read_b128 v[232:235], v210 offset:24576
	s_waitcnt lgkmcnt(10)
	v_mfma_f32_32x32x16_bf16 v[80:95], v[236:239], v[118:121], v[80:95]
	v_mfma_f32_32x32x16_bf16 v[64:79], v[240:243], v[118:121], v[64:79]
	ds_read_b128 v[236:239], v211 offset:16384
	ds_read_b128 v[240:243], v211 offset:24576
	s_waitcnt lgkmcnt(6)
	v_mfma_f32_32x32x16_bf16 v[80:95], v[150:153], v[114:117], v[80:95]
	v_mfma_f32_32x32x16_bf16 v[64:79], v[154:157], v[114:117], v[64:79]
	ds_read_b64_tr_b16 v[150:151], v196 offset:0
	ds_read_b64_tr_b16 v[152:153], v196 offset:2048
	ds_read_b64_tr_b16 v[154:155], v196 offset:4096
	ds_read_b64_tr_b16 v[156:157], v196 offset:6144
	s_waitcnt lgkmcnt(8)
	v_mfma_f32_32x32x16_bf16 v[80:95], v[158:161], v[110:113], v[80:95]
	v_mfma_f32_32x32x16_bf16 v[64:79], v[162:165], v[110:113], v[64:79]
	ds_read_b64_tr_b16 v[158:159], v196 offset:8192
	ds_read_b64_tr_b16 v[160:161], v196 offset:10240
	ds_read_b64_tr_b16 v[162:163], v196 offset:12288
	ds_read_b64_tr_b16 v[164:165], v196 offset:14336
	s_waitcnt lgkmcnt(10)
; #define SBAR() __builtin_amdgcn_sched_barrier(0)
; __device__ __forceinline__ void partialSM(f32x16& p0, f32x16& p1, float& m_reg, float& mn, float& alpha) {
;     ...
;   float pmax = p0[0];
; #pragma unroll
;   for (int r = 1; r < 16; ++r) pmax = fmaxf(pmax, p0[r]);
; #pragma unroll
;   for (int r = 0; r < 16; ++r) pmax = fmaxf(pmax, p1[r]);
;   { auto rr = __builtin_amdgcn_permlane32_swap(__float_as_uint(pmax), __float_as_uint(pmax), false, false);
;     pmax = fmaxf(__uint_as_float(rr[0]), __uint_as_float(rr[1])); }
;   if (__builtin_expect(__all(pmax - m_reg <= THR / SCALE), 1)) { mn = m_reg; alpha = 1.f; }
;   else { mn = fmaxf(m_reg, pmax); alpha = __builtin_amdgcn_exp2f((m_reg - mn) * C); m_reg = mn; }
; template <int D0> __device__ __forceinline__ void pv_one(f32x16& od, int vb, bf16x8 pa0, bf16x8 pa1, bf16x8 pa2, bf16x8 pa3) {
;   const s16x4 l0 = tr_read<v_rd_off(D0, 0, 0)>(vb), h0 = tr_read<v_rd_off(D0, 0, 1)>(vb), l1 = tr_read<v_rd_off(D0, 1, 0)>(vb), h1 = tr_read<v_rd_off(D0, 1, 1)>(vb);
;   const s16x4 l2 = tr_read<v_rd_off(D0, 2, 0)>(vb), h2 = tr_read<v_rd_off(D0, 2, 1)>(vb), l3 = tr_read<v_rd_off(D0, 3, 0)>(vb), h3 = tr_read<v_rd_off(D0, 3, 1)>(vb);
;   asm volatile("s_waitcnt lgkmcnt(0)" ::: "memory"); SBAR();
;     ...
;   od = __builtin_amdgcn_mfma_f32_32x32x16_bf16(pa0, PK(l0, h0), od, 0, 0, 0);
;   od = __builtin_amdgcn_mfma_f32_32x32x16_bf16(pa1, PK(l1, h1), od, 0, 0, 0);
;   od = __builtin_amdgcn_mfma_f32_32x32x16_bf16(pa2, PK(l2, h2), od, 0, 0, 0);
;   od = __builtin_amdgcn_mfma_f32_32x32x16_bf16(pa3, PK(l3, h3), od, 0, 0, 0);
;     ...
; }
; __device__ __forceinline__ void pv_d0(f32x16* o, int vb, bf16x8 pa0, bf16x8 pa1, bf16x8 pa2, bf16x8 pa3) {
;   pv_one<0>(o[0], vb, pa0, pa1, pa2, pa3); pv_one<1>(o[1], vb, pa0, pa1, pa2, pa3); pv_one<2>(o[2], vb, pa0, pa1, pa2, pa3); pv_one<3>(o[3], vb, pa0, pa1, pa2, pa3);
	v_mfma_f32_32x32x16_bf16 v[80:95], v[228:231], v[106:109], v[80:95]
	v_mfma_f32_32x32x16_bf16 v[64:79], v[232:235], v[106:109], v[64:79]
	ds_read_b64_tr_b16 v[228:229], v196 offset:512
	ds_read_b64_tr_b16 v[230:231], v196 offset:2560
	ds_read_b64_tr_b16 v[232:233], v196 offset:4608
	ds_read_b64_tr_b16 v[234:235], v196 offset:6656
	s_waitcnt lgkmcnt(12)
	v_mfma_f32_32x32x16_bf16 v[80:95], v[236:239], v[102:105], v[80:95]
	v_mfma_f32_32x32x16_bf16 v[64:79], v[240:243], v[102:105], v[64:79]
	ds_read_b64_tr_b16 v[236:237], v196 offset:8704
	ds_read_b64_tr_b16 v[238:239], v196 offset:10752
	s_waitcnt lgkmcnt(12)
	v_mfma_f32_32x32x16_bf16 v[0:15], v[166:169], v[150:153], v[0:15]
	ds_read_b64_tr_b16 v[240:241], v196 offset:12800
	ds_read_b64_tr_b16 v[242:243], v196 offset:14848
	s_waitcnt lgkmcnt(12)
	v_mfma_f32_32x32x16_bf16 v[0:15], v[170:173], v[154:157], v[0:15]
	ds_read_b64_tr_b16 v[150:151], v196 offset:1024
	ds_read_b64_tr_b16 v[152:153], v196 offset:3072
	s_waitcnt lgkmcnt(12)
	v_mfma_f32_32x32x16_bf16 v[0:15], v[176:179], v[158:161], v[0:15]
	ds_read_b64_tr_b16 v[154:155], v196 offset:5120
	ds_read_b64_tr_b16 v[156:157], v196 offset:7168
	s_waitcnt lgkmcnt(12)
	v_mfma_f32_32x32x16_bf16 v[0:15], v[180:183], v[162:165], v[0:15]
	ds_read_b64_tr_b16 v[158:159], v196 offset:9216
	ds_read_b64_tr_b16 v[160:161], v196 offset:11264
	s_waitcnt lgkmcnt(12)
	v_mfma_f32_32x32x16_bf16 v[48:63], v[166:169], v[228:231], v[48:63]
	ds_read_b64_tr_b16 v[162:163], v196 offset:13312
	ds_read_b64_tr_b16 v[164:165], v196 offset:15360
	s_waitcnt lgkmcnt(12)
	v_mfma_f32_32x32x16_bf16 v[48:63], v[170:173], v[232:235], v[48:63]
	ds_read_b64_tr_b16 v[228:229], v196 offset:1536
	ds_read_b64_tr_b16 v[230:231], v196 offset:3584
	s_waitcnt lgkmcnt(12)
	v_mfma_f32_32x32x16_bf16 v[48:63], v[176:179], v[236:239], v[48:63]
	ds_read_b64_tr_b16 v[232:233], v196 offset:5632
	ds_read_b64_tr_b16 v[234:235], v196 offset:7680
	s_waitcnt lgkmcnt(12)
	v_mfma_f32_32x32x16_bf16 v[48:63], v[180:183], v[240:243], v[48:63]
	ds_read_b64_tr_b16 v[236:237], v196 offset:9728
	ds_read_b64_tr_b16 v[238:239], v196 offset:11776
	s_waitcnt lgkmcnt(12)
	v_mfma_f32_32x32x16_bf16 v[32:47], v[166:169], v[150:153], v[32:47]
	ds_read_b64_tr_b16 v[240:241], v196 offset:13824
	ds_read_b64_tr_b16 v[242:243], v196 offset:15872
	s_waitcnt lgkmcnt(12)
	v_mfma_f32_32x32x16_bf16 v[32:47], v[170:173], v[154:157], v[32:47]
	s_waitcnt lgkmcnt(10)
	v_mfma_f32_32x32x16_bf16 v[32:47], v[176:179], v[158:161], v[32:47]
	s_waitcnt lgkmcnt(8)
	v_mfma_f32_32x32x16_bf16 v[32:47], v[180:183], v[162:165], v[32:47]
	s_waitcnt lgkmcnt(6)
	v_mfma_f32_32x32x16_bf16 v[16:31], v[166:169], v[228:231], v[16:31]
	s_waitcnt lgkmcnt(4)
	v_mfma_f32_32x32x16_bf16 v[16:31], v[170:173], v[232:235], v[16:31]
	s_waitcnt lgkmcnt(2)
	v_mfma_f32_32x32x16_bf16 v[16:31], v[176:179], v[236:239], v[16:31]
	s_waitcnt lgkmcnt(0)
	v_mfma_f32_32x32x16_bf16 v[16:31], v[180:183], v[240:243], v[16:31]
	s_setprio 0
	s_barrier
	v_max3_f32 v190, v80, v81, v82
	v_max3_f32 v191, v64, v65, v66
	v_max3_f32 v190, v190, v83, v84
	v_max3_f32 v191, v191, v67, v68
	v_max3_f32 v190, v190, v85, v86
	v_max3_f32 v191, v191, v69, v70
	v_max3_f32 v190, v190, v87, v88
	v_max3_f32 v191, v191, v71, v72
	v_max3_f32 v190, v190, v89, v90
	v_max3_f32 v191, v191, v73, v74
	v_max3_f32 v190, v190, v91, v92
	v_max3_f32 v191, v191, v75, v76
	v_max3_f32 v190, v190, v93, v94
	v_max3_f32 v191, v191, v77, v78
	v_max3_f32 v190, v190, v95, v79
	v_max_f32_e32 v190, v190, v191
	v_sub_f32_e32 v215, v190, v174
	v_cmp_ge_f32_e32 vcc, s86, v215
	s_nop 0
	s_cmp_eq_u64 vcc, exec
	s_cbranch_scc1 .Lda_common_1
	v_mov_b32_e32 v191, v190
	s_nop 1
	v_permlane32_swap_b32_e32 v190, v191
	s_nop 0
	v_max_f32_e32 v212, v190, v191
	v_max_f32_e32 v191, v174, v212
	v_sub_f32_e32 v215, v174, v191
	v_mul_f32_e32 v215, s92, v215
	v_exp_f32_e32 v213, v215
	v_mov_b32_e32 v174, v191
	v_mul_f32_e32 v214, 0xbe0293ee, v174
	v_mul_f32_e32 v175, v175, v213
	s_and_saveexec_b64 s[12:13], s[40:41]
	ds_write_b32 v199, v213 offset:128
	s_or_b64 exec, exec, s[12:13]
	s_waitcnt lgkmcnt(0)
	v_add_u32_e32 v215, v99, v96
	ds_read_b128 v[228:231], v215 offset:128
	ds_read_b128 v[232:235], v215 offset:160
	ds_read_b128 v[236:239], v215 offset:192
	ds_read_b128 v[240:243], v215 offset:224
	s_waitcnt lgkmcnt(0)
	v_pk_mul_f32 v[0:1], v[0:1], v[228:229]
	v_pk_mul_f32 v[2:3], v[2:3], v[230:231]
	v_pk_mul_f32 v[4:5], v[4:5], v[232:233]
	v_pk_mul_f32 v[6:7], v[6:7], v[234:235]
	v_pk_mul_f32 v[8:9], v[8:9], v[236:237]
	v_pk_mul_f32 v[10:11], v[10:11], v[238:239]
	v_pk_mul_f32 v[12:13], v[12:13], v[240:241]
	v_pk_mul_f32 v[14:15], v[14:15], v[242:243]
	v_pk_mul_f32 v[48:49], v[48:49], v[228:229]
	v_pk_mul_f32 v[50:51], v[50:51], v[230:231]
	v_pk_mul_f32 v[52:53], v[52:53], v[232:233]
	v_pk_mul_f32 v[54:55], v[54:55], v[234:235]
	v_pk_mul_f32 v[56:57], v[56:57], v[236:237]
	v_pk_mul_f32 v[58:59], v[58:59], v[238:239]
	v_pk_mul_f32 v[60:61], v[60:61], v[240:241]
	v_pk_mul_f32 v[62:63], v[62:63], v[242:243]
	v_pk_mul_f32 v[32:33], v[32:33], v[228:229]
	v_pk_mul_f32 v[34:35], v[34:35], v[230:231]
	v_pk_mul_f32 v[36:37], v[36:37], v[232:233]
	v_pk_mul_f32 v[38:39], v[38:39], v[234:235]
	v_pk_mul_f32 v[40:41], v[40:41], v[236:237]
	v_pk_mul_f32 v[42:43], v[42:43], v[238:239]
	v_pk_mul_f32 v[44:45], v[44:45], v[240:241]
	v_pk_mul_f32 v[46:47], v[46:47], v[242:243]
	v_pk_mul_f32 v[16:17], v[16:17], v[228:229]
	v_pk_mul_f32 v[18:19], v[18:19], v[230:231]
	v_pk_mul_f32 v[20:21], v[20:21], v[232:233]
	v_pk_mul_f32 v[22:23], v[22:23], v[234:235]
	v_pk_mul_f32 v[24:25], v[24:25], v[236:237]
	v_pk_mul_f32 v[26:27], v[26:27], v[238:239]
	v_pk_mul_f32 v[28:29], v[28:29], v[240:241]
	v_pk_mul_f32 v[30:31], v[30:31], v[242:243]

; __device__ __forceinline__ void partialSM(f32x16& p0, f32x16& p1, float& m_reg, float& mn, float& alpha) {
;     ...
;   for (int r = 0; r < 16; ++r) p0[r] = __builtin_amdgcn_exp2f(p0[r]);
; }
; __device__ __forceinline__ void finishSM(f32x16& p0, f32x16& p1, float alpha, float& l_reg, bf16x8& pa0, bf16x8& pa1, bf16x8& pa2, bf16x8& pa3) {
; #pragma unroll
;   for (int r = 0; r < 16; ++r) p1[r] = __builtin_amdgcn_exp2f(p1[r]);
;   float ps = 0;
; #pragma unroll
;   for (int r = 0; r < 16; ++r) ps += p0[r];
; #pragma unroll
;   for (int r = 0; r < 16; ++r) ps += p1[r];
;   { auto rr = __builtin_amdgcn_permlane32_swap(__float_as_uint(ps), __float_as_uint(ps), false, false);
;     ps = __uint_as_float(rr[0]) + __uint_as_float(rr[1]); }
;   l_reg = l_reg * alpha + ps;
;     ...
;   PK4(p0, 0, pa0); PK4(p0, 8, pa1); PK4(p1, 0, pa2); PK4(p1, 8, pa3);
;     ...
; }
; __device__ __forceinline__ void qkt(f32x16& p0, f32x16& p1, const bf16_t* Ks, const bf16x8* qr, int r32, int hi) {
;   p0 = f32x16{}; p1 = f32x16{};
; #pragma unroll
;   for (int d0 = 0; d0 < 8; ++d0) { int cb = (d0 * 16 + hi * 8) * 2;
;     bf16x8 b0 = *reinterpret_cast<const bf16x8*>((const char*)Ks + KSWZ(r32, cb));
;     bf16x8 b1 = *reinterpret_cast<const bf16x8*>((const char*)Ks + KSWZ(32 + r32, cb));
;     p0 = __builtin_amdgcn_mfma_f32_32x32x16_bf16(b0, qr[d0], p0, 0, 0, 0);
;     p1 = __builtin_amdgcn_mfma_f32_32x32x16_bf16(b1, qr[d0], p1, 0, 0, 0); }
; }
.Lda_noresc_1:
	s_cmp_lt_u32 s31, 131
	s_cbranch_scc0 .Lda_skipk_1
	ds_read_b128 v[150:153], v204 offset:32768
	ds_read_b128 v[154:157], v204 offset:40960
	ds_read_b128 v[158:161], v205 offset:32768
	ds_read_b128 v[162:165], v205 offset:40960
	ds_read_b128 v[228:231], v206 offset:32768
	ds_read_b128 v[232:235], v206 offset:40960
	ds_read_b128 v[236:239], v207 offset:32768
	ds_read_b128 v[240:243], v207 offset:40960
.Lda_skipk_1:
	v_exp_f32_e32 v80, v80
	v_exp_f32_e32 v81, v81
	v_exp_f32_e32 v82, v82
	v_exp_f32_e32 v83, v83
	v_exp_f32_e32 v84, v84
	v_exp_f32_e32 v85, v85
	v_exp_f32_e32 v86, v86
	v_exp_f32_e32 v87, v87
	v_exp_f32_e32 v88, v88
	v_exp_f32_e32 v89, v89
	v_exp_f32_e32 v90, v90
	v_exp_f32_e32 v91, v91
	v_exp_f32_e32 v92, v92
	v_exp_f32_e32 v93, v93
	v_exp_f32_e32 v94, v94
	v_exp_f32_e32 v95, v95
	v_exp_f32_e32 v64, v64
	v_exp_f32_e32 v65, v65
	v_exp_f32_e32 v66, v66
	v_exp_f32_e32 v67, v67
	v_exp_f32_e32 v68, v68
	v_exp_f32_e32 v69, v69
	v_exp_f32_e32 v70, v70
	v_exp_f32_e32 v71, v71
	v_exp_f32_e32 v72, v72
	v_exp_f32_e32 v73, v73
	v_exp_f32_e32 v74, v74
	v_exp_f32_e32 v75, v75
	v_exp_f32_e32 v76, v76
	v_exp_f32_e32 v77, v77
	v_exp_f32_e32 v78, v78
	v_exp_f32_e32 v79, v79
	v_add_f32_e32 v190, v80, v81
	v_add_f32_e32 v191, v82, v83
	v_add_f32_e32 v190, v190, v84
	v_add_f32_e32 v191, v191, v85
	v_add_f32_e32 v190, v190, v86
	v_add_f32_e32 v191, v191, v87
	v_add_f32_e32 v190, v190, v88
	v_add_f32_e32 v191, v191, v89
	v_add_f32_e32 v190, v190, v90
	v_add_f32_e32 v191, v191, v91
	v_add_f32_e32 v190, v190, v92
	v_add_f32_e32 v191, v191, v93
	v_add_f32_e32 v190, v190, v94
	v_add_f32_e32 v191, v191, v95
	v_add_f32_e32 v190, v190, v64
	v_add_f32_e32 v191, v191, v65
	v_add_f32_e32 v190, v190, v66
	v_add_f32_e32 v191, v191, v67
	v_add_f32_e32 v190, v190, v68
	v_add_f32_e32 v191, v191, v69
	v_add_f32_e32 v190, v190, v70
	v_add_f32_e32 v191, v191, v71
	v_add_f32_e32 v190, v190, v72
	v_add_f32_e32 v191, v191, v73
	v_add_f32_e32 v190, v190, v74
	v_add_f32_e32 v191, v191, v75
	v_add_f32_e32 v190, v190, v76
	v_add_f32_e32 v191, v191, v77
	v_add_f32_e32 v190, v190, v78
	v_add_f32_e32 v191, v191, v79
	v_add_f32_e32 v190, v190, v191
	v_cvt_pk_bf16_f32 v166, v80, v81
	v_cvt_pk_bf16_f32 v167, v82, v83
	v_cvt_pk_bf16_f32 v168, v84, v85
	v_cvt_pk_bf16_f32 v169, v86, v87
	v_cvt_pk_bf16_f32 v170, v88, v89
	v_cvt_pk_bf16_f32 v171, v90, v91
	v_cvt_pk_bf16_f32 v172, v92, v93
	v_cvt_pk_bf16_f32 v173, v94, v95
	v_cvt_pk_bf16_f32 v176, v64, v65
	v_cvt_pk_bf16_f32 v177, v66, v67
	v_cvt_pk_bf16_f32 v178, v68, v69
	v_cvt_pk_bf16_f32 v179, v70, v71
	v_cvt_pk_bf16_f32 v180, v72, v73
	v_cvt_pk_bf16_f32 v181, v74, v75
	v_cvt_pk_bf16_f32 v182, v76, v77
	v_cvt_pk_bf16_f32 v183, v78, v79
	v_permlane32_swap_b32_e32 v166, v168
	v_permlane32_swap_b32_e32 v167, v169
	v_permlane32_swap_b32_e32 v170, v172
	v_permlane32_swap_b32_e32 v171, v173
	v_permlane32_swap_b32_e32 v176, v178
	v_permlane32_swap_b32_e32 v177, v179
	v_permlane32_swap_b32_e32 v180, v182
	v_permlane32_swap_b32_e32 v181, v183
	v_add_f32_e32 v175, v175, v190
	s_add_u32 s31, s31, 1
	s_barrier
	s_setprio 3
	s_waitcnt vmcnt(4)
	ds_write_b128 v197, v[134:137] offset:0
	ds_write_b128 v197, v[138:141] offset:8192
	ds_write_b128 v185, v[142:145] offset:0
	ds_write_b128 v185, v[146:149] offset:8192
	s_waitcnt lgkmcnt(10)
	v_mfma_f32_32x32x16_bf16 v[80:95], v[150:153], v[130:133], 0
	v_mfma_f32_32x32x16_bf16 v[64:79], v[154:157], v[130:133], 0
	global_load_dwordx4 v[134:137], v184, s[16:17]
	global_load_dwordx4 v[138:141], v184, s[2:3]
	global_load_dwordx4 v[142:145], v184, s[14:15]
	global_load_dwordx4 v[146:149], v184, s[10:11]
	s_add_u32 s16, s16, 0x60000
	s_addc_u32 s17, s17, 0
	s_add_u32 s2, s2, 0x60000
	s_addc_u32 s3, s3, 0
	s_add_u32 s14, s14, 0x60000
	s_addc_u32 s15, s15, 0
	s_add_u32 s10, s10, 0x60000
	s_addc_u32 s11, s11, 0
	ds_read_b128 v[150:153], v208 offset:32768
	ds_read_b128 v[154:157], v208 offset:40960
	s_waitcnt lgkmcnt(10)
	v_mfma_f32_32x32x16_bf16 v[80:95], v[158:161], v[126:129], v[80:95]
	v_mfma_f32_32x32x16_bf16 v[64:79], v[162:165], v[126:129], v[64:79]
	ds_read_b128 v[158:161], v209 offset:32768
	ds_read_b128 v[162:165], v209 offset:40960
	s_waitcnt lgkmcnt(10)
	v_mfma_f32_32x32x16_bf16 v[80:95], v[228:231], v[122:125], v[80:95]
	v_mfma_f32_32x32x16_bf16 v[64:79], v[232:235], v[122:125], v[64:79]
	ds_read_b128 v[228:231], v210 offset:32768
	ds_read_b128 v[232:235], v210 offset:40960
	s_waitcnt lgkmcnt(10)
	v_mfma_f32_32x32x16_bf16 v[80:95], v[236:239], v[118:121], v[80:95]
	v_mfma_f32_32x32x16_bf16 v[64:79], v[240:243], v[118:121], v[64:79]
	ds_read_b128 v[236:239], v211 offset:32768
	ds_read_b128 v[240:243], v211 offset:40960
	s_waitcnt lgkmcnt(6)
	v_mfma_f32_32x32x16_bf16 v[80:95], v[150:153], v[114:117], v[80:95]
	v_mfma_f32_32x32x16_bf16 v[64:79], v[154:157], v[114:117], v[64:79]
	ds_read_b64_tr_b16 v[150:151], v196 offset:16384
	ds_read_b64_tr_b16 v[152:153], v196 offset:18432
	ds_read_b64_tr_b16 v[154:155], v196 offset:20480
	ds_read_b64_tr_b16 v[156:157], v196 offset:22528
	s_waitcnt lgkmcnt(8)
	v_mfma_f32_32x32x16_bf16 v[80:95], v[158:161], v[110:113], v[80:95]
	v_mfma_f32_32x32x16_bf16 v[64:79], v[162:165], v[110:113], v[64:79]
	ds_read_b64_tr_b16 v[158:159], v196 offset:24576
	ds_read_b64_tr_b16 v[160:161], v196 offset:26624
	ds_read_b64_tr_b16 v[162:163], v196 offset:28672
	ds_read_b64_tr_b16 v[164:165], v196 offset:30720
	s_waitcnt lgkmcnt(10)
; #define SBAR() __builtin_amdgcn_sched_barrier(0)
; __device__ __forceinline__ void partialSM(f32x16& p0, f32x16& p1, float& m_reg, float& mn, float& alpha) {
;     ...
;   float pmax = p0[0];
; #pragma unroll
;   for (int r = 1; r < 16; ++r) pmax = fmaxf(pmax, p0[r]);
; #pragma unroll
;   for (int r = 0; r < 16; ++r) pmax = fmaxf(pmax, p1[r]);
;   { auto rr = __builtin_amdgcn_permlane32_swap(__float_as_uint(pmax), __float_as_uint(pmax), false, false);
;     pmax = fmaxf(__uint_as_float(rr[0]), __uint_as_float(rr[1])); }
;   if (__builtin_expect(__all(pmax - m_reg <= THR / SCALE), 1)) { mn = m_reg; alpha = 1.f; }
;   else { mn = fmaxf(m_reg, pmax); alpha = __builtin_amdgcn_exp2f((m_reg - mn) * C); m_reg = mn; }
; template <int D0> __device__ __forceinline__ void pv_one(f32x16& od, int vb, bf16x8 pa0, bf16x8 pa1, bf16x8 pa2, bf16x8 pa3) {
;   const s16x4 l0 = tr_read<v_rd_off(D0, 0, 0)>(vb), h0 = tr_read<v_rd_off(D0, 0, 1)>(vb), l1 = tr_read<v_rd_off(D0, 1, 0)>(vb), h1 = tr_read<v_rd_off(D0, 1, 1)>(vb);
;   const s16x4 l2 = tr_read<v_rd_off(D0, 2, 0)>(vb), h2 = tr_read<v_rd_off(D0, 2, 1)>(vb), l3 = tr_read<v_rd_off(D0, 3, 0)>(vb), h3 = tr_read<v_rd_off(D0, 3, 1)>(vb);
;   asm volatile("s_waitcnt lgkmcnt(0)" ::: "memory"); SBAR();
;     ...
;   od = __builtin_amdgcn_mfma_f32_32x32x16_bf16(pa0, PK(l0, h0), od, 0, 0, 0);
;   od = __builtin_amdgcn_mfma_f32_32x32x16_bf16(pa1, PK(l1, h1), od, 0, 0, 0);
;   od = __builtin_amdgcn_mfma_f32_32x32x16_bf16(pa2, PK(l2, h2), od, 0, 0, 0);
;   od = __builtin_amdgcn_mfma_f32_32x32x16_bf16(pa3, PK(l3, h3), od, 0, 0, 0);
;     ...
; }
; __device__ __forceinline__ void pv_d0(f32x16* o, int vb, bf16x8 pa0, bf16x8 pa1, bf16x8 pa2, bf16x8 pa3) {
;   pv_one<0>(o[0], vb, pa0, pa1, pa2, pa3); pv_one<1>(o[1], vb, pa0, pa1, pa2, pa3); pv_one<2>(o[2], vb, pa0, pa1, pa2, pa3); pv_one<3>(o[3], vb, pa0, pa1, pa2, pa3);
	v_mfma_f32_32x32x16_bf16 v[80:95], v[228:231], v[106:109], v[80:95]
	v_mfma_f32_32x32x16_bf16 v[64:79], v[232:235], v[106:109], v[64:79]
	ds_read_b64_tr_b16 v[228:229], v196 offset:16896
	ds_read_b64_tr_b16 v[230:231], v196 offset:18944
	ds_read_b64_tr_b16 v[232:233], v196 offset:20992
	ds_read_b64_tr_b16 v[234:235], v196 offset:23040
	s_waitcnt lgkmcnt(12)
	v_mfma_f32_32x32x16_bf16 v[80:95], v[236:239], v[102:105], v[80:95]
	v_mfma_f32_32x32x16_bf16 v[64:79], v[240:243], v[102:105], v[64:79]
	ds_read_b64_tr_b16 v[236:237], v196 offset:25088
	ds_read_b64_tr_b16 v[238:239], v196 offset:27136
	s_waitcnt lgkmcnt(12)
	v_mfma_f32_32x32x16_bf16 v[0:15], v[166:169], v[150:153], v[0:15]
	ds_read_b64_tr_b16 v[240:241], v196 offset:29184
	ds_read_b64_tr_b16 v[242:243], v196 offset:31232
	s_waitcnt lgkmcnt(12)
	v_mfma_f32_32x32x16_bf16 v[0:15], v[170:173], v[154:157], v[0:15]
	ds_read_b64_tr_b16 v[150:151], v196 offset:17408
	ds_read_b64_tr_b16 v[152:153], v196 offset:19456
	s_waitcnt lgkmcnt(12)
	v_mfma_f32_32x32x16_bf16 v[0:15], v[176:179], v[158:161], v[0:15]
	ds_read_b64_tr_b16 v[154:155], v196 offset:21504
	ds_read_b64_tr_b16 v[156:157], v196 offset:23552
	s_waitcnt lgkmcnt(12)
	v_mfma_f32_32x32x16_bf16 v[0:15], v[180:183], v[162:165], v[0:15]
	ds_read_b64_tr_b16 v[158:159], v196 offset:25600
	ds_read_b64_tr_b16 v[160:161], v196 offset:27648
	s_waitcnt lgkmcnt(12)
	v_mfma_f32_32x32x16_bf16 v[48:63], v[166:169], v[228:231], v[48:63]
	ds_read_b64_tr_b16 v[162:163], v196 offset:29696
	ds_read_b64_tr_b16 v[164:165], v196 offset:31744
	s_waitcnt lgkmcnt(12)
	v_mfma_f32_32x32x16_bf16 v[48:63], v[170:173], v[232:235], v[48:63]
	ds_read_b64_tr_b16 v[228:229], v196 offset:17920
	ds_read_b64_tr_b16 v[230:231], v196 offset:19968
	s_waitcnt lgkmcnt(12)
	v_mfma_f32_32x32x16_bf16 v[48:63], v[176:179], v[236:239], v[48:63]
	ds_read_b64_tr_b16 v[232:233], v196 offset:22016
	ds_read_b64_tr_b16 v[234:235], v196 offset:24064
	s_waitcnt lgkmcnt(12)
	v_mfma_f32_32x32x16_bf16 v[48:63], v[180:183], v[240:243], v[48:63]
	ds_read_b64_tr_b16 v[236:237], v196 offset:26112
	ds_read_b64_tr_b16 v[238:239], v196 offset:28160
	s_waitcnt lgkmcnt(12)
	v_mfma_f32_32x32x16_bf16 v[32:47], v[166:169], v[150:153], v[32:47]
	ds_read_b64_tr_b16 v[240:241], v196 offset:30208
	ds_read_b64_tr_b16 v[242:243], v196 offset:32256
	s_waitcnt lgkmcnt(12)
	v_mfma_f32_32x32x16_bf16 v[32:47], v[170:173], v[154:157], v[32:47]
	s_waitcnt lgkmcnt(10)
	v_mfma_f32_32x32x16_bf16 v[32:47], v[176:179], v[158:161], v[32:47]
	s_waitcnt lgkmcnt(8)
	v_mfma_f32_32x32x16_bf16 v[32:47], v[180:183], v[162:165], v[32:47]
	s_waitcnt lgkmcnt(6)
	v_mfma_f32_32x32x16_bf16 v[16:31], v[166:169], v[228:231], v[16:31]
	s_waitcnt lgkmcnt(4)
	v_mfma_f32_32x32x16_bf16 v[16:31], v[170:173], v[232:235], v[16:31]
	s_waitcnt lgkmcnt(2)
	v_mfma_f32_32x32x16_bf16 v[16:31], v[176:179], v[236:239], v[16:31]
	s_waitcnt lgkmcnt(0)
	v_mfma_f32_32x32x16_bf16 v[16:31], v[180:183], v[240:243], v[16:31]
	s_setprio 0
	s_barrier
	v_max3_f32 v190, v80, v81, v82
	v_max3_f32 v191, v64, v65, v66
	v_max3_f32 v190, v190, v83, v84
	v_max3_f32 v191, v191, v67, v68
	v_max3_f32 v190, v190, v85, v86
	v_max3_f32 v191, v191, v69, v70
	v_max3_f32 v190, v190, v87, v88
	v_max3_f32 v191, v191, v71, v72
	v_max3_f32 v190, v190, v89, v90
	v_max3_f32 v191, v191, v73, v74
	v_max3_f32 v190, v190, v91, v92
	v_max3_f32 v191, v191, v75, v76
	v_max3_f32 v190, v190, v93, v94
	v_max3_f32 v191, v191, v77, v78
	v_max3_f32 v190, v190, v95, v79
	v_max_f32_e32 v190, v190, v191
	v_sub_f32_e32 v215, v190, v174
	v_cmp_ge_f32_e32 vcc, s86, v215
	s_nop 0
	s_cmp_eq_u64 vcc, exec
	s_cbranch_scc1 .Lda_common_2
	v_mov_b32_e32 v191, v190
	s_nop 1
	v_permlane32_swap_b32_e32 v190, v191
	s_nop 0
	v_max_f32_e32 v212, v190, v191
	v_max_f32_e32 v191, v174, v212
	v_sub_f32_e32 v215, v174, v191
	v_mul_f32_e32 v215, s92, v215
	v_exp_f32_e32 v213, v215
	v_mov_b32_e32 v174, v191
	v_mul_f32_e32 v214, 0xbe0293ee, v174
	v_mul_f32_e32 v175, v175, v213
	s_and_saveexec_b64 s[12:13], s[40:41]
	ds_write_b32 v199, v213 offset:128
	s_or_b64 exec, exec, s[12:13]
	s_waitcnt lgkmcnt(0)
	v_add_u32_e32 v215, v99, v96
	ds_read_b128 v[228:231], v215 offset:128
	ds_read_b128 v[232:235], v215 offset:160
	ds_read_b128 v[236:239], v215 offset:192
	ds_read_b128 v[240:243], v215 offset:224
	s_waitcnt lgkmcnt(0)
	v_pk_mul_f32 v[0:1], v[0:1], v[228:229]
	v_pk_mul_f32 v[2:3], v[2:3], v[230:231]
	v_pk_mul_f32 v[4:5], v[4:5], v[232:233]
	v_pk_mul_f32 v[6:7], v[6:7], v[234:235]
	v_pk_mul_f32 v[8:9], v[8:9], v[236:237]
	v_pk_mul_f32 v[10:11], v[10:11], v[238:239]
	v_pk_mul_f32 v[12:13], v[12:13], v[240:241]
	v_pk_mul_f32 v[14:15], v[14:15], v[242:243]
	v_pk_mul_f32 v[48:49], v[48:49], v[228:229]
	v_pk_mul_f32 v[50:51], v[50:51], v[230:231]
	v_pk_mul_f32 v[52:53], v[52:53], v[232:233]
	v_pk_mul_f32 v[54:55], v[54:55], v[234:235]
	v_pk_mul_f32 v[56:57], v[56:57], v[236:237]
	v_pk_mul_f32 v[58:59], v[58:59], v[238:239]
	v_pk_mul_f32 v[60:61], v[60:61], v[240:241]
	v_pk_mul_f32 v[62:63], v[62:63], v[242:243]
	v_pk_mul_f32 v[32:33], v[32:33], v[228:229]
	v_pk_mul_f32 v[34:35], v[34:35], v[230:231]
	v_pk_mul_f32 v[36:37], v[36:37], v[232:233]
	v_pk_mul_f32 v[38:39], v[38:39], v[234:235]
	v_pk_mul_f32 v[40:41], v[40:41], v[236:237]
	v_pk_mul_f32 v[42:43], v[42:43], v[238:239]
	v_pk_mul_f32 v[44:45], v[44:45], v[240:241]
	v_pk_mul_f32 v[46:47], v[46:47], v[242:243]
	v_pk_mul_f32 v[16:17], v[16:17], v[228:229]
	v_pk_mul_f32 v[18:19], v[18:19], v[230:231]
	v_pk_mul_f32 v[20:21], v[20:21], v[232:233]
	v_pk_mul_f32 v[22:23], v[22:23], v[234:235]
	v_pk_mul_f32 v[24:25], v[24:25], v[236:237]
	v_pk_mul_f32 v[26:27], v[26:27], v[238:239]
	v_pk_mul_f32 v[28:29], v[28:29], v[240:241]
	v_pk_mul_f32 v[30:31], v[30:31], v[242:243]

; __device__ __forceinline__ void partialSM(f32x16& p0, f32x16& p1, float& m_reg, float& mn, float& alpha) {
;     ...
;   for (int r = 0; r < 16; ++r) p0[r] = __builtin_amdgcn_exp2f(p0[r]);
; }
; __device__ __forceinline__ void finishSM(f32x16& p0, f32x16& p1, float alpha, float& l_reg, bf16x8& pa0, bf16x8& pa1, bf16x8& pa2, bf16x8& pa3) {
; #pragma unroll
;   for (int r = 0; r < 16; ++r) p1[r] = __builtin_amdgcn_exp2f(p1[r]);
;   float ps = 0;
; #pragma unroll
;   for (int r = 0; r < 16; ++r) ps += p0[r];
; #pragma unroll
;   for (int r = 0; r < 16; ++r) ps += p1[r];
;   { auto rr = __builtin_amdgcn_permlane32_swap(__float_as_uint(ps), __float_as_uint(ps), false, false);
;     ps = __uint_as_float(rr[0]) + __uint_as_float(rr[1]); }
;   l_reg = l_reg * alpha + ps;
;     ...
;   PK4(p0, 0, pa0); PK4(p0, 8, pa1); PK4(p1, 0, pa2); PK4(p1, 8, pa3);
;     ...
; }
; __device__ __forceinline__ void qkt(f32x16& p0, f32x16& p1, const bf16_t* Ks, const bf16x8* qr, int r32, int hi) {
;   p0 = f32x16{}; p1 = f32x16{};
; #pragma unroll
;   for (int d0 = 0; d0 < 8; ++d0) { int cb = (d0 * 16 + hi * 8) * 2;
;     bf16x8 b0 = *reinterpret_cast<const bf16x8*>((const char*)Ks + KSWZ(r32, cb));
;     bf16x8 b1 = *reinterpret_cast<const bf16x8*>((const char*)Ks + KSWZ(32 + r32, cb));
;     p0 = __builtin_amdgcn_mfma_f32_32x32x16_bf16(b0, qr[d0], p0, 0, 0, 0);
;     p1 = __builtin_amdgcn_mfma_f32_32x32x16_bf16(b1, qr[d0], p1, 0, 0, 0); }
; }
.Lda_noresc_2:
	s_cmp_lt_u32 s31, 131
	s_cbranch_scc0 .Lda_skipk_2
	ds_read_b128 v[150:153], v204 offset:49152
	ds_read_b128 v[154:157], v204 offset:57344
	ds_read_b128 v[158:161], v205 offset:49152
	ds_read_b128 v[162:165], v205 offset:57344
	ds_read_b128 v[228:231], v206 offset:49152
	ds_read_b128 v[232:235], v206 offset:57344
	ds_read_b128 v[236:239], v207 offset:49152
	ds_read_b128 v[240:243], v207 offset:57344
.Lda_skipk_2:
	v_exp_f32_e32 v80, v80
	v_exp_f32_e32 v81, v81
	v_exp_f32_e32 v82, v82
	v_exp_f32_e32 v83, v83
	v_exp_f32_e32 v84, v84
	v_exp_f32_e32 v85, v85
	v_exp_f32_e32 v86, v86
	v_exp_f32_e32 v87, v87
	v_exp_f32_e32 v88, v88
	v_exp_f32_e32 v89, v89
	v_exp_f32_e32 v90, v90
	v_exp_f32_e32 v91, v91
	v_exp_f32_e32 v92, v92
	v_exp_f32_e32 v93, v93
	v_exp_f32_e32 v94, v94
	v_exp_f32_e32 v95, v95
	v_exp_f32_e32 v64, v64
	v_exp_f32_e32 v65, v65
	v_exp_f32_e32 v66, v66
	v_exp_f32_e32 v67, v67
	v_exp_f32_e32 v68, v68
	v_exp_f32_e32 v69, v69
	v_exp_f32_e32 v70, v70
	v_exp_f32_e32 v71, v71
	v_exp_f32_e32 v72, v72
	v_exp_f32_e32 v73, v73
	v_exp_f32_e32 v74, v74
	v_exp_f32_e32 v75, v75
	v_exp_f32_e32 v76, v76
	v_exp_f32_e32 v77, v77
	v_exp_f32_e32 v78, v78
	v_exp_f32_e32 v79, v79
	v_add_f32_e32 v190, v80, v81
	v_add_f32_e32 v191, v82, v83
	v_add_f32_e32 v190, v190, v84
	v_add_f32_e32 v191, v191, v85
	v_add_f32_e32 v190, v190, v86
	v_add_f32_e32 v191, v191, v87
	v_add_f32_e32 v190, v190, v88
	v_add_f32_e32 v191, v191, v89
	v_add_f32_e32 v190, v190, v90
	v_add_f32_e32 v191, v191, v91
	v_add_f32_e32 v190, v190, v92
	v_add_f32_e32 v191, v191, v93
	v_add_f32_e32 v190, v190, v94
	v_add_f32_e32 v191, v191, v95
	v_add_f32_e32 v190, v190, v64
	v_add_f32_e32 v191, v191, v65
	v_add_f32_e32 v190, v190, v66
	v_add_f32_e32 v191, v191, v67
	v_add_f32_e32 v190, v190, v68
	v_add_f32_e32 v191, v191, v69
	v_add_f32_e32 v190, v190, v70
	v_add_f32_e32 v191, v191, v71
	v_add_f32_e32 v190, v190, v72
	v_add_f32_e32 v191, v191, v73
	v_add_f32_e32 v190, v190, v74
	v_add_f32_e32 v191, v191, v75
	v_add_f32_e32 v190, v190, v76
	v_add_f32_e32 v191, v191, v77
	v_add_f32_e32 v190, v190, v78
	v_add_f32_e32 v191, v191, v79
	v_add_f32_e32 v190, v190, v191
	v_cvt_pk_bf16_f32 v166, v80, v81
	v_cvt_pk_bf16_f32 v167, v82, v83
	v_cvt_pk_bf16_f32 v168, v84, v85
	v_cvt_pk_bf16_f32 v169, v86, v87
	v_cvt_pk_bf16_f32 v170, v88, v89
	v_cvt_pk_bf16_f32 v171, v90, v91
	v_cvt_pk_bf16_f32 v172, v92, v93
	v_cvt_pk_bf16_f32 v173, v94, v95
	v_cvt_pk_bf16_f32 v176, v64, v65
	v_cvt_pk_bf16_f32 v177, v66, v67
	v_cvt_pk_bf16_f32 v178, v68, v69
	v_cvt_pk_bf16_f32 v179, v70, v71
	v_cvt_pk_bf16_f32 v180, v72, v73
	v_cvt_pk_bf16_f32 v181, v74, v75
	v_cvt_pk_bf16_f32 v182, v76, v77
	v_cvt_pk_bf16_f32 v183, v78, v79
	v_permlane32_swap_b32_e32 v166, v168
	v_permlane32_swap_b32_e32 v167, v169
	v_permlane32_swap_b32_e32 v170, v172
	v_permlane32_swap_b32_e32 v171, v173
	v_permlane32_swap_b32_e32 v176, v178
	v_permlane32_swap_b32_e32 v177, v179
	v_permlane32_swap_b32_e32 v180, v182
	v_permlane32_swap_b32_e32 v181, v183
	v_add_f32_e32 v175, v175, v190
	s_add_u32 s31, s31, 1
	s_barrier
	s_setprio 3
	s_waitcnt vmcnt(4)
	ds_write_b128 v197, v[186:189] offset:16384
	ds_write_b128 v197, v[220:223] offset:24576
	ds_write_b128 v185, v[246:249] offset:16384
	ds_write_b128 v185, v[200:203] offset:24576
	s_waitcnt lgkmcnt(10)
	v_mfma_f32_32x32x16_bf16 v[80:95], v[150:153], v[130:133], 0
	v_mfma_f32_32x32x16_bf16 v[64:79], v[154:157], v[130:133], 0
	global_load_dwordx4 v[186:189], v184, s[16:17]
	global_load_dwordx4 v[220:223], v184, s[2:3]
	global_load_dwordx4 v[246:249], v184, s[14:15]
	global_load_dwordx4 v[200:203], v184, s[10:11]
	s_add_u32 s16, s16, 0x60000
	s_addc_u32 s17, s17, 0
	s_add_u32 s2, s2, 0x60000
	s_addc_u32 s3, s3, 0
	s_add_u32 s14, s14, 0x60000
	s_addc_u32 s15, s15, 0
	s_add_u32 s10, s10, 0x60000
	s_addc_u32 s11, s11, 0
	ds_read_b128 v[150:153], v208 offset:49152
	ds_read_b128 v[154:157], v208 offset:57344
	s_waitcnt lgkmcnt(10)
	v_mfma_f32_32x32x16_bf16 v[80:95], v[158:161], v[126:129], v[80:95]
	v_mfma_f32_32x32x16_bf16 v[64:79], v[162:165], v[126:129], v[64:79]
	ds_read_b128 v[158:161], v209 offset:49152
	ds_read_b128 v[162:165], v209 offset:57344
	s_waitcnt lgkmcnt(10)
	v_mfma_f32_32x32x16_bf16 v[80:95], v[228:231], v[122:125], v[80:95]
	v_mfma_f32_32x32x16_bf16 v[64:79], v[232:235], v[122:125], v[64:79]
	ds_read_b128 v[228:231], v210 offset:49152
	ds_read_b128 v[232:235], v210 offset:57344
	s_waitcnt lgkmcnt(10)
	v_mfma_f32_32x32x16_bf16 v[80:95], v[236:239], v[118:121], v[80:95]
	v_mfma_f32_32x32x16_bf16 v[64:79], v[240:243], v[118:121], v[64:79]
	ds_read_b128 v[236:239], v211 offset:49152
	ds_read_b128 v[240:243], v211 offset:57344
	s_waitcnt lgkmcnt(6)
	v_mfma_f32_32x32x16_bf16 v[80:95], v[150:153], v[114:117], v[80:95]
	v_mfma_f32_32x32x16_bf16 v[64:79], v[154:157], v[114:117], v[64:79]
	ds_read_b64_tr_b16 v[150:151], v196 offset:32768
	ds_read_b64_tr_b16 v[152:153], v196 offset:34816
	ds_read_b64_tr_b16 v[154:155], v196 offset:36864
	ds_read_b64_tr_b16 v[156:157], v196 offset:38912
	s_waitcnt lgkmcnt(8)
	v_mfma_f32_32x32x16_bf16 v[80:95], v[158:161], v[110:113], v[80:95]
	v_mfma_f32_32x32x16_bf16 v[64:79], v[162:165], v[110:113], v[64:79]
	ds_read_b64_tr_b16 v[158:159], v196 offset:40960
	ds_read_b64_tr_b16 v[160:161], v196 offset:43008
	ds_read_b64_tr_b16 v[162:163], v196 offset:45056
	ds_read_b64_tr_b16 v[164:165], v196 offset:47104
	s_waitcnt lgkmcnt(10)
; #define SBAR() __builtin_amdgcn_sched_barrier(0)
; __device__ __forceinline__ void partialSM(f32x16& p0, f32x16& p1, float& m_reg, float& mn, float& alpha) {
;     ...
;   float pmax = p0[0];
; #pragma unroll
;   for (int r = 1; r < 16; ++r) pmax = fmaxf(pmax, p0[r]);
; #pragma unroll
;   for (int r = 0; r < 16; ++r) pmax = fmaxf(pmax, p1[r]);
;   { auto rr = __builtin_amdgcn_permlane32_swap(__float_as_uint(pmax), __float_as_uint(pmax), false, false);
;     pmax = fmaxf(__uint_as_float(rr[0]), __uint_as_float(rr[1])); }
;   if (__builtin_expect(__all(pmax - m_reg <= THR / SCALE), 1)) { mn = m_reg; alpha = 1.f; }
;   else { mn = fmaxf(m_reg, pmax); alpha = __builtin_amdgcn_exp2f((m_reg - mn) * C); m_reg = mn; }
; template <int D0> __device__ __forceinline__ void pv_one(f32x16& od, int vb, bf16x8 pa0, bf16x8 pa1, bf16x8 pa2, bf16x8 pa3) {
;   const s16x4 l0 = tr_read<v_rd_off(D0, 0, 0)>(vb), h0 = tr_read<v_rd_off(D0, 0, 1)>(vb), l1 = tr_read<v_rd_off(D0, 1, 0)>(vb), h1 = tr_read<v_rd_off(D0, 1, 1)>(vb);
;   const s16x4 l2 = tr_read<v_rd_off(D0, 2, 0)>(vb), h2 = tr_read<v_rd_off(D0, 2, 1)>(vb), l3 = tr_read<v_rd_off(D0, 3, 0)>(vb), h3 = tr_read<v_rd_off(D0, 3, 1)>(vb);
;   asm volatile("s_waitcnt lgkmcnt(0)" ::: "memory"); SBAR();
;     ...
;   od = __builtin_amdgcn_mfma_f32_32x32x16_bf16(pa0, PK(l0, h0), od, 0, 0, 0);
;   od = __builtin_amdgcn_mfma_f32_32x32x16_bf16(pa1, PK(l1, h1), od, 0, 0, 0);
;   od = __builtin_amdgcn_mfma_f32_32x32x16_bf16(pa2, PK(l2, h2), od, 0, 0, 0);
;   od = __builtin_amdgcn_mfma_f32_32x32x16_bf16(pa3, PK(l3, h3), od, 0, 0, 0);
;     ...
; }
; __device__ __forceinline__ void pv_d0(f32x16* o, int vb, bf16x8 pa0, bf16x8 pa1, bf16x8 pa2, bf16x8 pa3) {
;   pv_one<0>(o[0], vb, pa0, pa1, pa2, pa3); pv_one<1>(o[1], vb, pa0, pa1, pa2, pa3); pv_one<2>(o[2], vb, pa0, pa1, pa2, pa3); pv_one<3>(o[3], vb, pa0, pa1, pa2, pa3);
	v_mfma_f32_32x32x16_bf16 v[80:95], v[228:231], v[106:109], v[80:95]
	v_mfma_f32_32x32x16_bf16 v[64:79], v[232:235], v[106:109], v[64:79]
	ds_read_b64_tr_b16 v[228:229], v196 offset:33280
	ds_read_b64_tr_b16 v[230:231], v196 offset:35328
	ds_read_b64_tr_b16 v[232:233], v196 offset:37376
	ds_read_b64_tr_b16 v[234:235], v196 offset:39424
	s_waitcnt lgkmcnt(12)
	v_mfma_f32_32x32x16_bf16 v[80:95], v[236:239], v[102:105], v[80:95]
	v_mfma_f32_32x32x16_bf16 v[64:79], v[240:243], v[102:105], v[64:79]
	ds_read_b64_tr_b16 v[236:237], v196 offset:41472
	ds_read_b64_tr_b16 v[238:239], v196 offset:43520
	s_waitcnt lgkmcnt(12)
	v_mfma_f32_32x32x16_bf16 v[0:15], v[166:169], v[150:153], v[0:15]
	ds_read_b64_tr_b16 v[240:241], v196 offset:45568
	ds_read_b64_tr_b16 v[242:243], v196 offset:47616
	s_waitcnt lgkmcnt(12)
	v_mfma_f32_32x32x16_bf16 v[0:15], v[170:173], v[154:157], v[0:15]
	ds_read_b64_tr_b16 v[150:151], v196 offset:33792
	ds_read_b64_tr_b16 v[152:153], v196 offset:35840
	s_waitcnt lgkmcnt(12)
	v_mfma_f32_32x32x16_bf16 v[0:15], v[176:179], v[158:161], v[0:15]
	ds_read_b64_tr_b16 v[154:155], v196 offset:37888
	ds_read_b64_tr_b16 v[156:157], v196 offset:39936
	s_waitcnt lgkmcnt(12)
	v_mfma_f32_32x32x16_bf16 v[0:15], v[180:183], v[162:165], v[0:15]
	ds_read_b64_tr_b16 v[158:159], v196 offset:41984
	ds_read_b64_tr_b16 v[160:161], v196 offset:44032
	s_waitcnt lgkmcnt(12)
	v_mfma_f32_32x32x16_bf16 v[48:63], v[166:169], v[228:231], v[48:63]
	ds_read_b64_tr_b16 v[162:163], v196 offset:46080
	ds_read_b64_tr_b16 v[164:165], v196 offset:48128
	s_waitcnt lgkmcnt(12)
	v_mfma_f32_32x32x16_bf16 v[48:63], v[170:173], v[232:235], v[48:63]
	ds_read_b64_tr_b16 v[228:229], v196 offset:34304
	ds_read_b64_tr_b16 v[230:231], v196 offset:36352
	s_waitcnt lgkmcnt(12)
	v_mfma_f32_32x32x16_bf16 v[48:63], v[176:179], v[236:239], v[48:63]
	ds_read_b64_tr_b16 v[232:233], v196 offset:38400
	ds_read_b64_tr_b16 v[234:235], v196 offset:40448
	s_waitcnt lgkmcnt(12)
	v_mfma_f32_32x32x16_bf16 v[48:63], v[180:183], v[240:243], v[48:63]
	ds_read_b64_tr_b16 v[236:237], v196 offset:42496
	ds_read_b64_tr_b16 v[238:239], v196 offset:44544
	s_waitcnt lgkmcnt(12)
	v_mfma_f32_32x32x16_bf16 v[32:47], v[166:169], v[150:153], v[32:47]
	ds_read_b64_tr_b16 v[240:241], v196 offset:46592
	ds_read_b64_tr_b16 v[242:243], v196 offset:48640
	s_waitcnt lgkmcnt(12)
	v_mfma_f32_32x32x16_bf16 v[32:47], v[170:173], v[154:157], v[32:47]
	s_waitcnt lgkmcnt(10)
	v_mfma_f32_32x32x16_bf16 v[32:47], v[176:179], v[158:161], v[32:47]
	s_waitcnt lgkmcnt(8)
	v_mfma_f32_32x32x16_bf16 v[32:47], v[180:183], v[162:165], v[32:47]
	s_waitcnt lgkmcnt(6)
	v_mfma_f32_32x32x16_bf16 v[16:31], v[166:169], v[228:231], v[16:31]
	s_waitcnt lgkmcnt(4)
	v_mfma_f32_32x32x16_bf16 v[16:31], v[170:173], v[232:235], v[16:31]
	s_waitcnt lgkmcnt(2)
	v_mfma_f32_32x32x16_bf16 v[16:31], v[176:179], v[236:239], v[16:31]
	s_waitcnt lgkmcnt(0)
	v_mfma_f32_32x32x16_bf16 v[16:31], v[180:183], v[240:243], v[16:31]
	s_setprio 0
	s_barrier
	v_max3_f32 v190, v80, v81, v82
	v_max3_f32 v191, v64, v65, v66
	v_max3_f32 v190, v190, v83, v84
	v_max3_f32 v191, v191, v67, v68
	v_max3_f32 v190, v190, v85, v86
	v_max3_f32 v191, v191, v69, v70
	v_max3_f32 v190, v190, v87, v88
	v_max3_f32 v191, v191, v71, v72
	v_max3_f32 v190, v190, v89, v90
	v_max3_f32 v191, v191, v73, v74
	v_max3_f32 v190, v190, v91, v92
	v_max3_f32 v191, v191, v75, v76
	v_max3_f32 v190, v190, v93, v94
	v_max3_f32 v191, v191, v77, v78
	v_max3_f32 v190, v190, v95, v79
	v_max_f32_e32 v190, v190, v191
	v_sub_f32_e32 v215, v190, v174
	v_cmp_ge_f32_e32 vcc, s86, v215
	s_nop 0
	s_cmp_eq_u64 vcc, exec
	s_cbranch_scc1 .Lda_common_3
	v_mov_b32_e32 v191, v190
	s_nop 1
	v_permlane32_swap_b32_e32 v190, v191
	s_nop 0
	v_max_f32_e32 v212, v190, v191
	v_max_f32_e32 v191, v174, v212
	v_sub_f32_e32 v215, v174, v191
	v_mul_f32_e32 v215, s92, v215
	v_exp_f32_e32 v213, v215
	v_mov_b32_e32 v174, v191
	v_mul_f32_e32 v214, 0xbe0293ee, v174
	v_mul_f32_e32 v175, v175, v213
	s_and_saveexec_b64 s[12:13], s[40:41]
	ds_write_b32 v199, v213 offset:128
	s_or_b64 exec, exec, s[12:13]
	s_waitcnt lgkmcnt(0)
	v_add_u32_e32 v215, v99, v96
	ds_read_b128 v[228:231], v215 offset:128
	ds_read_b128 v[232:235], v215 offset:160
	ds_read_b128 v[236:239], v215 offset:192
	ds_read_b128 v[240:243], v215 offset:224
	s_waitcnt lgkmcnt(0)
	v_pk_mul_f32 v[0:1], v[0:1], v[228:229]
	v_pk_mul_f32 v[2:3], v[2:3], v[230:231]
	v_pk_mul_f32 v[4:5], v[4:5], v[232:233]
	v_pk_mul_f32 v[6:7], v[6:7], v[234:235]
	v_pk_mul_f32 v[8:9], v[8:9], v[236:237]
	v_pk_mul_f32 v[10:11], v[10:11], v[238:239]
	v_pk_mul_f32 v[12:13], v[12:13], v[240:241]
	v_pk_mul_f32 v[14:15], v[14:15], v[242:243]
	v_pk_mul_f32 v[48:49], v[48:49], v[228:229]
	v_pk_mul_f32 v[50:51], v[50:51], v[230:231]
	v_pk_mul_f32 v[52:53], v[52:53], v[232:233]
	v_pk_mul_f32 v[54:55], v[54:55], v[234:235]
	v_pk_mul_f32 v[56:57], v[56:57], v[236:237]
	v_pk_mul_f32 v[58:59], v[58:59], v[238:239]
	v_pk_mul_f32 v[60:61], v[60:61], v[240:241]
	v_pk_mul_f32 v[62:63], v[62:63], v[242:243]
	v_pk_mul_f32 v[32:33], v[32:33], v[228:229]
	v_pk_mul_f32 v[34:35], v[34:35], v[230:231]
	v_pk_mul_f32 v[36:37], v[36:37], v[232:233]
	v_pk_mul_f32 v[38:39], v[38:39], v[234:235]
	v_pk_mul_f32 v[40:41], v[40:41], v[236:237]
	v_pk_mul_f32 v[42:43], v[42:43], v[238:239]
	v_pk_mul_f32 v[44:45], v[44:45], v[240:241]
	v_pk_mul_f32 v[46:47], v[46:47], v[242:243]
	v_pk_mul_f32 v[16:17], v[16:17], v[228:229]
	v_pk_mul_f32 v[18:19], v[18:19], v[230:231]
	v_pk_mul_f32 v[20:21], v[20:21], v[232:233]
	v_pk_mul_f32 v[22:23], v[22:23], v[234:235]
	v_pk_mul_f32 v[24:25], v[24:25], v[236:237]
	v_pk_mul_f32 v[26:27], v[26:27], v[238:239]
	v_pk_mul_f32 v[28:29], v[28:29], v[240:241]
	v_pk_mul_f32 v[30:31], v[30:31], v[242:243]

; #define SBAR() __builtin_amdgcn_sched_barrier(0)
; __device__ __forceinline__ void partialSM(f32x16& p0, f32x16& p1, float& m_reg, float& mn, float& alpha) {
;     ...
;   for (int r = 0; r < 16; ++r) p0[r] = __builtin_amdgcn_exp2f(p0[r]);
; }
; __device__ __forceinline__ void finishSM(f32x16& p0, f32x16& p1, float alpha, float& l_reg, bf16x8& pa0, bf16x8& pa1, bf16x8& pa2, bf16x8& pa3) {
; #pragma unroll
;   for (int r = 0; r < 16; ++r) p1[r] = __builtin_amdgcn_exp2f(p1[r]);
;   float ps = 0;
; #pragma unroll
;   for (int r = 0; r < 16; ++r) ps += p0[r];
; #pragma unroll
;   for (int r = 0; r < 16; ++r) ps += p1[r];
;   { auto rr = __builtin_amdgcn_permlane32_swap(__float_as_uint(ps), __float_as_uint(ps), false, false);
;     ps = __uint_as_float(rr[0]) + __uint_as_float(rr[1]); }
;   l_reg = l_reg * alpha + ps;
;     ...
;   PK4(p0, 0, pa0); PK4(p0, 8, pa1); PK4(p1, 0, pa2); PK4(p1, 8, pa3);
;     ...
; }
; template <int D0> __device__ __forceinline__ void pv_one(f32x16& od, int vb, bf16x8 pa0, bf16x8 pa1, bf16x8 pa2, bf16x8 pa3) {
;   const s16x4 l0 = tr_read<v_rd_off(D0, 0, 0)>(vb), h0 = tr_read<v_rd_off(D0, 0, 1)>(vb), l1 = tr_read<v_rd_off(D0, 1, 0)>(vb), h1 = tr_read<v_rd_off(D0, 1, 1)>(vb);
;   const s16x4 l2 = tr_read<v_rd_off(D0, 2, 0)>(vb), h2 = tr_read<v_rd_off(D0, 2, 1)>(vb), l3 = tr_read<v_rd_off(D0, 3, 0)>(vb), h3 = tr_read<v_rd_off(D0, 3, 1)>(vb);
;   asm volatile("s_waitcnt lgkmcnt(0)" ::: "memory"); SBAR();
;     ...
;   od = __builtin_amdgcn_mfma_f32_32x32x16_bf16(pa0, PK(l0, h0), od, 0, 0, 0);
;   od = __builtin_amdgcn_mfma_f32_32x32x16_bf16(pa1, PK(l1, h1), od, 0, 0, 0);
;   od = __builtin_amdgcn_mfma_f32_32x32x16_bf16(pa2, PK(l2, h2), od, 0, 0, 0);
;   od = __builtin_amdgcn_mfma_f32_32x32x16_bf16(pa3, PK(l3, h3), od, 0, 0, 0);
;     ...
; }
; __device__ __forceinline__ void pv_d0(f32x16* o, int vb, bf16x8 pa0, bf16x8 pa1, bf16x8 pa2, bf16x8 pa3) {
;   pv_one<0>(o[0], vb, pa0, pa1, pa2, pa3); pv_one<1>(o[1], vb, pa0, pa1, pa2, pa3); pv_one<2>(o[2], vb, pa0, pa1, pa2, pa3); pv_one<3>(o[3], vb, pa0, pa1, pa2, pa3);
.Lda_noresc_3:
	s_cmp_lt_u32 s31, 131
	s_cbranch_scc0 .Lda_skipk_3
	ds_read_b128 v[150:153], v204 offset:0
	ds_read_b128 v[154:157], v204 offset:8192
	ds_read_b128 v[158:161], v205 offset:0
	ds_read_b128 v[162:165], v205 offset:8192
	ds_read_b128 v[228:231], v206 offset:0
	ds_read_b128 v[232:235], v206 offset:8192
	ds_read_b128 v[236:239], v207 offset:0
	ds_read_b128 v[240:243], v207 offset:8192
.Lda_skipk_3:
	v_exp_f32_e32 v80, v80
	v_exp_f32_e32 v81, v81
	v_exp_f32_e32 v82, v82
	v_exp_f32_e32 v83, v83
	v_exp_f32_e32 v84, v84
	v_exp_f32_e32 v85, v85
	v_exp_f32_e32 v86, v86
	v_exp_f32_e32 v87, v87
	v_exp_f32_e32 v88, v88
	v_exp_f32_e32 v89, v89
	v_exp_f32_e32 v90, v90
	v_exp_f32_e32 v91, v91
	v_exp_f32_e32 v92, v92
	v_exp_f32_e32 v93, v93
	v_exp_f32_e32 v94, v94
	v_exp_f32_e32 v95, v95
	v_exp_f32_e32 v64, v64
	v_exp_f32_e32 v65, v65
	v_exp_f32_e32 v66, v66
	v_exp_f32_e32 v67, v67
	v_exp_f32_e32 v68, v68
	v_exp_f32_e32 v69, v69
	v_exp_f32_e32 v70, v70
	v_exp_f32_e32 v71, v71
	v_exp_f32_e32 v72, v72
	v_exp_f32_e32 v73, v73
	v_exp_f32_e32 v74, v74
	v_exp_f32_e32 v75, v75
	v_exp_f32_e32 v76, v76
	v_exp_f32_e32 v77, v77
	v_exp_f32_e32 v78, v78
	v_exp_f32_e32 v79, v79
	v_add_f32_e32 v190, v80, v81
	v_add_f32_e32 v191, v82, v83
	v_add_f32_e32 v190, v190, v84
	v_add_f32_e32 v191, v191, v85
	v_add_f32_e32 v190, v190, v86
	v_add_f32_e32 v191, v191, v87
	v_add_f32_e32 v190, v190, v88
	v_add_f32_e32 v191, v191, v89
	v_add_f32_e32 v190, v190, v90
	v_add_f32_e32 v191, v191, v91
	v_add_f32_e32 v190, v190, v92
	v_add_f32_e32 v191, v191, v93
	v_add_f32_e32 v190, v190, v94
	v_add_f32_e32 v191, v191, v95
	v_add_f32_e32 v190, v190, v64
	v_add_f32_e32 v191, v191, v65
	v_add_f32_e32 v190, v190, v66
	v_add_f32_e32 v191, v191, v67
	v_add_f32_e32 v190, v190, v68
	v_add_f32_e32 v191, v191, v69
	v_add_f32_e32 v190, v190, v70
	v_add_f32_e32 v191, v191, v71
	v_add_f32_e32 v190, v190, v72
	v_add_f32_e32 v191, v191, v73
	v_add_f32_e32 v190, v190, v74
	v_add_f32_e32 v191, v191, v75
	v_add_f32_e32 v190, v190, v76
	v_add_f32_e32 v191, v191, v77
	v_add_f32_e32 v190, v190, v78
	v_add_f32_e32 v191, v191, v79
	v_add_f32_e32 v190, v190, v191
	v_cvt_pk_bf16_f32 v166, v80, v81
	v_cvt_pk_bf16_f32 v167, v82, v83
	v_cvt_pk_bf16_f32 v168, v84, v85
	v_cvt_pk_bf16_f32 v169, v86, v87
	v_cvt_pk_bf16_f32 v170, v88, v89
	v_cvt_pk_bf16_f32 v171, v90, v91
	v_cvt_pk_bf16_f32 v172, v92, v93
	v_cvt_pk_bf16_f32 v173, v94, v95
	v_cvt_pk_bf16_f32 v176, v64, v65
	v_cvt_pk_bf16_f32 v177, v66, v67
	v_cvt_pk_bf16_f32 v178, v68, v69
	v_cvt_pk_bf16_f32 v179, v70, v71
	v_cvt_pk_bf16_f32 v180, v72, v73
	v_cvt_pk_bf16_f32 v181, v74, v75
	v_cvt_pk_bf16_f32 v182, v76, v77
	v_cvt_pk_bf16_f32 v183, v78, v79
	v_permlane32_swap_b32_e32 v166, v168
	v_permlane32_swap_b32_e32 v167, v169
	v_permlane32_swap_b32_e32 v170, v172
	v_permlane32_swap_b32_e32 v171, v173
	v_permlane32_swap_b32_e32 v176, v178
	v_permlane32_swap_b32_e32 v177, v179
	v_permlane32_swap_b32_e32 v180, v182
	v_permlane32_swap_b32_e32 v181, v183
	v_add_f32_e32 v175, v175, v190
	s_add_u32 s31, s31, 1
	s_barrier
	s_cmp_lt_u32 s31, 132
	s_cbranch_scc1 .Lda_loop
	s_setprio 3
	ds_read_b64_tr_b16 v[150:151], v196 offset:49152
	ds_read_b64_tr_b16 v[152:153], v196 offset:51200
	ds_read_b64_tr_b16 v[154:155], v196 offset:53248
	ds_read_b64_tr_b16 v[156:157], v196 offset:55296
	ds_read_b64_tr_b16 v[158:159], v196 offset:57344
	ds_read_b64_tr_b16 v[160:161], v196 offset:59392
	ds_read_b64_tr_b16 v[162:163], v196 offset:61440
	ds_read_b64_tr_b16 v[164:165], v196 offset:63488
	ds_read_b64_tr_b16 v[228:229], v196 offset:49664
	ds_read_b64_tr_b16 v[230:231], v196 offset:51712
	ds_read_b64_tr_b16 v[232:233], v196 offset:53760
	ds_read_b64_tr_b16 v[234:235], v196 offset:55808
	ds_read_b64_tr_b16 v[236:237], v196 offset:57856
	ds_read_b64_tr_b16 v[238:239], v196 offset:59904
	s_waitcnt lgkmcnt(12)
	v_mfma_f32_32x32x16_bf16 v[0:15], v[166:169], v[150:153], v[0:15]
	ds_read_b64_tr_b16 v[240:241], v196 offset:61952
	ds_read_b64_tr_b16 v[242:243], v196 offset:64000
	s_waitcnt lgkmcnt(12)
	v_mfma_f32_32x32x16_bf16 v[0:15], v[170:173], v[154:157], v[0:15]
	ds_read_b64_tr_b16 v[150:151], v196 offset:50176
	ds_read_b64_tr_b16 v[152:153], v196 offset:52224
	s_waitcnt lgkmcnt(12)
	v_mfma_f32_32x32x16_bf16 v[0:15], v[176:179], v[158:161], v[0:15]
	ds_read_b64_tr_b16 v[154:155], v196 offset:54272
	ds_read_b64_tr_b16 v[156:157], v196 offset:56320
	s_waitcnt lgkmcnt(12)
	v_mfma_f32_32x32x16_bf16 v[0:15], v[180:183], v[162:165], v[0:15]
	ds_read_b64_tr_b16 v[158:159], v196 offset:58368
	ds_read_b64_tr_b16 v[160:161], v196 offset:60416
	s_waitcnt lgkmcnt(12)
	v_mfma_f32_32x32x16_bf16 v[48:63], v[166:169], v[228:231], v[48:63]
	ds_read_b64_tr_b16 v[162:163], v196 offset:62464
	ds_read_b64_tr_b16 v[164:165], v196 offset:64512
	s_waitcnt lgkmcnt(12)
	v_mfma_f32_32x32x16_bf16 v[48:63], v[170:173], v[232:235], v[48:63]
	ds_read_b64_tr_b16 v[228:229], v196 offset:50688
	ds_read_b64_tr_b16 v[230:231], v196 offset:52736
	s_waitcnt lgkmcnt(12)
	v_mfma_f32_32x32x16_bf16 v[48:63], v[176:179], v[236:239], v[48:63]
	ds_read_b64_tr_b16 v[232:233], v196 offset:54784
	ds_read_b64_tr_b16 v[234:235], v196 offset:56832
	s_waitcnt lgkmcnt(12)
	v_mfma_f32_32x32x16_bf16 v[48:63], v[180:183], v[240:243], v[48:63]
	ds_read_b64_tr_b16 v[236:237], v196 offset:58880
	ds_read_b64_tr_b16 v[238:239], v196 offset:60928
	s_waitcnt lgkmcnt(12)
	v_mfma_f32_32x32x16_bf16 v[32:47], v[166:169], v[150:153], v[32:47]
	ds_read_b64_tr_b16 v[240:241], v196 offset:62976
	ds_read_b64_tr_b16 v[242:243], v196 offset:65024
	s_waitcnt lgkmcnt(12)
	v_mfma_f32_32x32x16_bf16 v[32:47], v[170:173], v[154:157], v[32:47]
	s_waitcnt lgkmcnt(10)
	v_mfma_f32_32x32x16_bf16 v[32:47], v[176:179], v[158:161], v[32:47]
	s_waitcnt lgkmcnt(8)
	v_mfma_f32_32x32x16_bf16 v[32:47], v[180:183], v[162:165], v[32:47]
	s_waitcnt lgkmcnt(6)
	v_mfma_f32_32x32x16_bf16 v[16:31], v[166:169], v[228:231], v[16:31]
	s_waitcnt lgkmcnt(4)
	v_mfma_f32_32x32x16_bf16 v[16:31], v[170:173], v[232:235], v[16:31]
	s_waitcnt lgkmcnt(2)
	v_mfma_f32_32x32x16_bf16 v[16:31], v[176:179], v[236:239], v[16:31]
	s_waitcnt lgkmcnt(0)
	v_mfma_f32_32x32x16_bf16 v[16:31], v[180:183], v[240:243], v[16:31]
	s_nop 12
	s_setprio 0
	s_cmp_lt_u32 s36, 4
	s_cbranch_scc0 .Lda_trail
	s_barrier
